# static s_setprio 1 at flash-loop entry moved to the first resident workgroup of each CU (blockIdx < 256) instead of the second
# baseline (speedup 1.0000x reference)
.LBB0_850:
	s_and_b64 s[2:3], s[10:11], exec
	v_readlane_b32 s2, v251, 29
	v_readlane_b32 s3, v251, 30
	s_cselect_b32 s2, s22, 0
	v_writelane_b32 v251, s2, 29
	v_mov_b32_e32 v0, v206
	v_mov_b32_e32 v79, 0
	v_writelane_b32 v251, s3, 30
	s_cmp_gt_u32 s2, s23
	v_mov_b32_e32 v78, 0
	v_mov_b32_e32 v77, 0
	v_mov_b32_e32 v76, 0
	v_mov_b32_e32 v75, 0
	v_mov_b32_e32 v74, 0
	v_mov_b32_e32 v73, 0
	v_mov_b32_e32 v72, 0
	v_mov_b32_e32 v71, 0
	v_mov_b32_e32 v70, 0
	v_mov_b32_e32 v69, 0
	v_mov_b32_e32 v68, 0
	v_mov_b32_e32 v67, 0
	v_mov_b32_e32 v66, 0
	v_mov_b32_e32 v65, 0
	v_mov_b32_e32 v64, 0
	v_mov_b32_e32 v63, 0
	v_mov_b32_e32 v62, 0
	v_mov_b32_e32 v61, 0
	v_mov_b32_e32 v60, 0
	v_mov_b32_e32 v59, 0
	v_mov_b32_e32 v58, 0
	v_mov_b32_e32 v57, 0
	v_mov_b32_e32 v56, 0
	v_mov_b32_e32 v55, 0
	v_mov_b32_e32 v54, 0
	v_mov_b32_e32 v53, 0
	v_mov_b32_e32 v52, 0
	v_mov_b32_e32 v51, 0
	v_mov_b32_e32 v50, 0
	v_mov_b32_e32 v49, 0
	v_mov_b32_e32 v48, 0
	v_mov_b32_e32 v202, 0
	s_cbranch_scc1 .LBB0_869
	v_readlane_b32 s48, v249, 26
	s_lshl_b64 s[14:15], s[0:1], 1
	v_readlane_b32 s50, v249, 28
	v_readlane_b32 s51, v249, 29
	s_add_u32 s0, s50, s14
	s_addc_u32 s1, s51, s15
	v_ashrrev_i32_e32 v8, 4, v0
	s_add_u32 s0, s0, s6
	v_ashrrev_i32_e32 v2, 3, v0
	v_ashrrev_i32_e32 v9, 31, v8
	s_addc_u32 s1, s1, s7
	v_ashrrev_i32_e32 v3, 31, v2
	v_lshlrev_b32_e32 v1, 4, v0
	v_lshlrev_b64 v[10:11], 8, v[8:9]
	v_readlane_b32 s16, v251, 29
	s_and_b64 s[2:3], s[10:11], exec
	v_lshlrev_b64 v[4:5], 7, v[2:3]
	v_lshl_add_u64 v[12:13], s[0:1], 0, v[10:11]
	v_and_b32_e32 v14, 0xf0, v1
	v_mov_b32_e32 v15, v33
	v_readlane_b32 s17, v251, 30
	s_cselect_b32 s25, s24, -1
	v_lshl_add_u64 v[6:7], s[0:1], 0, v[4:5]
	v_lshl_add_u64 v[12:13], v[12:13], 0, v[14:15]
	s_lshl_b64 s[0:1], s[16:17], 14
	v_lshl_add_u64 v[12:13], v[12:13], 0, s[0:1]
	s_mov_b32 s2, 0x803000
	v_add_co_u32_e32 v16, vcc, s2, v12
	s_mov_b32 s2, 0x802000
	s_nop 0
	v_addc_co_u32_e32 v17, vcc, 0, v13, vcc
	v_add_co_u32_e32 v18, vcc, s2, v12
	s_mov_b32 s2, 0x801000
	s_nop 0
	v_addc_co_u32_e32 v19, vcc, 0, v13, vcc
	global_load_dwordx4 v[148:151], v[16:17], off
	global_load_dwordx4 v[152:155], v[18:19], off
	v_add_co_u32_e32 v16, vcc, s2, v12
	v_and_b32_e32 v32, 0x70, v1
	s_nop 0
	v_addc_co_u32_e32 v17, vcc, 0, v13, vcc
	s_mov_b32 s2, 0x800000
	v_lshl_add_u64 v[6:7], v[6:7], 0, v[32:33]
	v_add_co_u32_e32 v12, vcc, s2, v12
	v_lshl_add_u64 v[6:7], v[6:7], 0, s[0:1]
	s_nop 0
	v_addc_co_u32_e32 v13, vcc, 0, v13, vcc
	s_movk_i32 s2, 0x3000
	global_load_dwordx4 v[136:139], v[16:17], off
	global_load_dwordx4 v[140:143], v[12:13], off
	v_add_co_u32_e32 v12, vcc, s2, v6
	s_movk_i32 s2, 0x2000
	s_nop 0
	v_addc_co_u32_e32 v13, vcc, 0, v7, vcc
	v_add_co_u32_e32 v16, vcc, s2, v6
	s_movk_i32 s2, 0x1000
	s_nop 0
	v_addc_co_u32_e32 v17, vcc, 0, v7, vcc
	v_add_co_u32_e32 v18, vcc, s2, v6
	v_mad_u64_u32 v[188:189], s[2:3], v2, s30, v[32:33]
	s_nop 0
	v_addc_co_u32_e32 v19, vcc, 0, v7, vcc
	global_load_dwordx4 v[144:147], v[16:17], off
	global_load_dwordx4 v[132:135], v[18:19], off
	global_load_dwordx4 v[156:159], v[12:13], off
	global_load_dwordx4 v[128:131], v[6:7], off
	v_and_b32_e32 v1, 31, v0
	v_lshrrev_b32_e32 v2, 1, v0
	s_movk_i32 s2, 0x108
	v_and_b32_e32 v6, 16, v2
	v_mul_u32_u24_e32 v7, 0x90, v1
	v_lshrrev_b32_e32 v2, 3, v0
	v_mul_u32_u24_e32 v1, 0x84, v1
	v_mad_u64_u32 v[190:191], s[2:3], v8, s2, v[14:15]
	v_and_b32_e32 v8, 4, v2
	v_lshlrev_b32_e32 v1, 1, v1
	v_lshl_add_u32 v167, v8, 1, v1
	v_lshl_add_u64 v[2:3], s[0:1], 0, v[4:5]
	v_and_b32_e32 v1, 7, v0
	v_lshl_or_b32 v2, v1, 4, v2
	v_lshl_add_u64 v[192:193], s[8:9], 0, v[2:3]
	v_lshl_add_u64 v[2:3], s[0:1], 0, v[10:11]
	v_and_b32_e32 v0, 15, v0
	v_mov_b32_e32 v46, v33
	v_mov_b32_e32 v47, v33
	v_lshl_or_b32 v2, v0, 4, v2
	v_sub_u32_e32 v0, v160, v8
	s_lshl_b32 s0, s16, 7
	v_mov_b32_e32 v32, v33
	v_mov_b32_e32 v34, v33
	v_mov_b32_e32 v35, v33
	v_mov_b32_e32 v36, v33
	v_mov_b32_e32 v37, v33
	v_mov_b32_e32 v38, v33
	v_mov_b32_e32 v39, v33
	v_mov_b32_e32 v40, v33
	v_mov_b32_e32 v41, v33
	v_mov_b32_e32 v42, v33
	v_mov_b32_e32 v43, v33
	v_mov_b32_e32 v44, v33
	v_mov_b32_e32 v45, v33
	v_mov_b64_e32 v[62:63], v[46:47]
	v_mov_b64_e32 v[78:79], v[46:47]
	v_lshl_add_u64 v[194:195], s[8:9], 0, v[2:3]
	s_lshl_b32 s26, s16, 1
	v_subrev_u32_e32 v189, s0, v0
	s_or_b32 s27, s0, 0x7f
	v_mov_b32_e32 v201, 0xf149f2ca
	v_mov_b32_e32 v202, 0
	v_add_u32_e32 v191, v6, v7
	v_mov_b64_e32 v[60:61], v[44:45]
	v_mov_b64_e32 v[58:59], v[42:43]
	v_mov_b64_e32 v[56:57], v[40:41]
	v_mov_b64_e32 v[54:55], v[38:39]
	v_mov_b64_e32 v[52:53], v[36:37]
	v_mov_b64_e32 v[50:51], v[34:35]
	v_mov_b64_e32 v[48:49], v[32:33]
	v_mov_b64_e32 v[76:77], v[44:45]
	v_mov_b64_e32 v[74:75], v[42:43]
	v_mov_b64_e32 v[72:73], v[40:41]
	v_mov_b64_e32 v[70:71], v[38:39]
	v_mov_b64_e32 v[68:69], v[36:37]
	v_mov_b64_e32 v[66:67], v[34:35]
	v_mov_b64_e32 v[64:65], v[32:33]
	v_readlane_b32 s49, v249, 27
	v_readlane_b32 s52, v249, 30
	v_readlane_b32 s53, v249, 31
	v_readlane_b32 s54, v249, 32
	v_readlane_b32 s55, v249, 33
	v_readlane_b32 s56, v249, 34
	v_readlane_b32 s57, v249, 35
	v_readlane_b32 s58, v249, 36
	v_readlane_b32 s59, v249, 37
	v_readlane_b32 s60, v249, 38
	v_readlane_b32 s61, v249, 39
	v_readlane_b32 s62, v249, 40
	v_readlane_b32 s63, v249, 41
	v_readlane_b32 s0, v250, 54
	s_nop 0
	s_cmpk_lt_u32 s0, 0x400
	s_cbranch_scc0 .Lfp_skip
	s_setprio 1
